# static s_setprio 1 for waves 4-7 through the GLA summary / attention / scan / GLA output phases
# baseline (speedup 1.0000x reference)
; __device__ void phase_gla_summ(const P& p) {
;   int tid = opaque_tid(p);
;   int u = blockIdx.x;
;   if (u >= 4096) return;
;   SummRaw cur = gla_summ_load(p, u, tid);
;   for (; u < 4096; u += gridDim.x) {
;     int un = u + gridDim.x;
;     SummRaw nxt = gla_summ_load(p, un < 4096 ? un : u, tid);
.LBB0_222:
	s_or_b64 exec, exec, s[0:1]
	s_cmpk_lt_u32 s33, 0x100
	s_cbranch_scc1 .Lmy_prio_done
	s_setprio 1
.Lmy_prio_done:
	s_cmpk_lt_i32 s2, 0x1000
	s_cselect_b64 s[6:7], -1, 0
	s_cmpk_gt_i32 s2, 0xfff
	s_waitcnt lgkmcnt(0)
	s_barrier
	v_mbcnt_lo_u32_b32 v16, -1, 0
	v_mbcnt_hi_u32_b32 v16, -1, v16
	s_cbranch_scc1 .LBB0_229
	v_add_u32_e32 v0, s33, v16
	v_readlane_b32 s3, v255, 1
	v_ashrrev_i32_e32 v33, 3, v0
	s_and_b32 s0, s3, 0xffffffc0
	v_lshlrev_b32_e32 v17, 3, v0
	v_add_u32_e32 v0, s0, v33
	v_ashrrev_i32_e32 v1, 31, v0
	s_lshl_b32 s0, s2, 6
	v_and_b32_e32 v32, 56, v17
	v_lshlrev_b64 v[0:1], 8, v[0:1]
	s_and_b32 s0, s0, 0xc0
	v_or3_b32 v0, v0, s0, v32
	v_lshlrev_b64 v[0:1], 1, v[0:1]
	v_lshl_add_u64 v[8:9], s[12:13], 0, v[0:1]
	v_lshl_add_u64 v[10:11], s[14:15], 0, v[0:1]
	global_load_dwordx4 v[4:7], v[8:9], off
	global_load_dwordx4 v[0:3], v[10:11], off
	s_add_u32 s4, s34, 0x16000000
	v_bfi_b32 v8, 63, v16, s3
	s_addc_u32 s5, s35, 0
	v_ashrrev_i32_e32 v9, 31, v8
	s_ashr_i32 s3, s2, 31
	v_lshlrev_b64 v[8:9], 9, v[8:9]
	s_lshl_b32 s0, s0, 1
	s_lshl_b64 s[8:9], s[2:3], 14
	s_mov_b32 s1, 0
	v_lshl_add_u64 v[8:9], s[4:5], 0, v[8:9]
	v_and_b32_e32 v36, -8, v33
	s_add_u32 s8, s18, s8
	v_lshlrev_b32_e32 v38, 6, v33
	v_lshl_add_u64 v[8:9], v[8:9], 0, s[0:1]
	v_ashrrev_i32_e32 v37, 31, v36
	s_addc_u32 s9, s19, s9
	v_ashrrev_i32_e32 v39, 31, v38
	v_mov_b32_e32 v35, 0
	v_lshl_add_u64 v[12:13], v[36:37], 1, v[8:9]
	v_lshl_add_u64 v[8:9], v[38:39], 1, s[8:9]
	v_lshlrev_b32_e32 v34, 1, v32
	v_lshl_add_u64 v[14:15], v[8:9], 0, v[34:35]
	global_load_dwordx4 v[28:31], v[12:13], off
	global_load_dwordx4 v[8:11], v[14:15], off
	v_and_b32_e32 v12, 0xffffffc0, v17
	v_add_u32_e32 v40, 0x1000, v12
	v_ashrrev_i32_e32 v41, 31, v40
	v_lshl_add_u64 v[12:13], v[40:41], 1, s[8:9]
	v_lshl_add_u64 v[12:13], v[12:13], 0, v[34:35]
	global_load_dwordx4 v[12:15], v[12:13], off
	s_add_u32 s8, s34, 0x1f400000
	s_addc_u32 s9, s35, 0
	s_add_u32 s10, s50, 4
	v_and_b32_e32 v46, 63, v16
	s_addc_u32 s11, s51, 0
	s_lshl_b32 s20, s2, 1
	s_lshl_b32 s3, s70, 1
	s_movk_i32 s28, 0x41
	s_movk_i32 s29, 0x820
	s_movk_i32 s30, 0x104
	s_add_i32 s31, 16, 0x18800
	s_movk_i32 s40, 0x100
	s_movk_i32 s41, 0x240
	s_movk_i32 s42, 0x48
	s_movk_i32 s43, 0x90
	s_add_i32 s44, 16, 0x11200
	s_movk_i32 s45, 0x80
	s_mov_b64 s[22:23], 0x800
	v_mov_b32_e32 v47, 0x4100
	v_mov_b32_e32 v48, 0x3ffc
	v_mov_b32_e32 v49, 0xa600
	v_mov_b32_e32 v50, 0x8200
	s_mov_b32 s21, s2
